# four big-GEMM K-loop headers aligned to 64 B (s_nop padding executed once per loop entry), on top of the previous best
# speedup vs baseline: 1.0025x; 1.0025x over previous
; template <class Epi, class Sched, bool ALIGN_EPI = false, bool SP2 = false>
; __device__ __forceinline__ void gemm_phase(PG8_LAS unsigned char* lds, const Gemm g, const Sched& S, const Epi& E) {
;     ...
;         const bool has_next = S.next(ui + 1, nxt);
;         const char* nA = has_next ? (const char*)g.A + (size_t)nxt.pm * tstep : cA; const char* nB = has_next ? (const char*)g.Bt + (size_t)nxt.pn * tstep : cB;
;         for (int t = 0; t < nt; t += 2) {
;             const bool last = (t == nt - 2);
;             const char* a1 = cA + (size_t)(t + 1) * kstep;
;             const char* a2 = last ? nA : cA + (size_t)(t + 2) * kstep; const char* b2 = last ? nB : cB + (size_t)(t + 2) * kstep;
;             const char* a3 = a2 + kstep; const char* b3 = b2 + kstep;
;     ...
; #pragma unroll
;         for (int a = 0; a < 2; ++a)
; #pragma unroll
;             for (int b = 0; b < 2; ++b)
; #pragma unroll
;                 for (int m = 0; m < 4; ++m)
; #pragma unroll
;                     for (int n = 0; n < 2; ++n) acc[a][b][m][n] = (f32x4){0.f, 0.f, 0.f, 0.f};
.LBB0_252:
	s_ashr_i32 s21, s20, 31
	s_lshl_b64 s[22:23], s[20:21], 20
	s_add_u32 s22, s33, s22
	s_addc_u32 s23, s36, s23
	s_and_b64 s[24:25], s[0:1], exec
	s_cselect_b32 s3, s23, s29
	s_cselect_b32 s21, s22, s28
	s_ashr_i32 s19, s18, 31
	s_lshl_b64 s[24:25], s[18:19], 20
	s_add_u32 s24, s6, s24
	s_addc_u32 s25, s7, s25
	s_and_b64 s[34:35], s[0:1], exec
	s_cselect_b32 s19, s25, s31
	s_cselect_b32 s27, s24, s30
	s_add_u32 s28, s28, 0x80080
	s_addc_u32 s29, s29, 0
	s_add_u32 s54, s30, 0x100
	v_mov_b32_e32 v0, 0
	s_addc_u32 s55, s31, 0
	s_mov_b32 s56, -2
	v_mov_b32_e32 v1, v0
	v_mov_b32_e32 v2, v0
	v_mov_b32_e32 v3, v0
	v_mov_b32_e32 v4, v0
	v_mov_b32_e32 v5, v0
	v_mov_b32_e32 v6, v0
	v_mov_b32_e32 v7, v0
	v_mov_b32_e32 v8, v0
	v_mov_b32_e32 v9, v0
	v_mov_b32_e32 v10, v0
	v_mov_b32_e32 v11, v0
	v_mov_b32_e32 v12, v0
	v_mov_b32_e32 v13, v0
	v_mov_b32_e32 v14, v0
	v_mov_b32_e32 v15, v0
	v_mov_b32_e32 v16, v0
	v_mov_b32_e32 v17, v0
	v_mov_b32_e32 v18, v0
	v_mov_b32_e32 v19, v0
	v_mov_b32_e32 v20, v0
	v_mov_b32_e32 v21, v0
	v_mov_b32_e32 v22, v0
	v_mov_b32_e32 v23, v0
	v_mov_b32_e32 v24, v0
	v_mov_b32_e32 v25, v0
	v_mov_b32_e32 v26, v0
	v_mov_b32_e32 v27, v0
	v_mov_b32_e32 v28, v0
	v_mov_b32_e32 v29, v0
	v_mov_b32_e32 v30, v0
	v_mov_b32_e32 v31, v0
	v_mov_b32_e32 v32, v0
	v_mov_b32_e32 v33, v0
	v_mov_b32_e32 v34, v0
	v_mov_b32_e32 v35, v0
	v_mov_b32_e32 v36, v0
	v_mov_b32_e32 v37, v0
	v_mov_b32_e32 v38, v0
	v_mov_b32_e32 v39, v0
	v_mov_b32_e32 v40, v0
	v_mov_b32_e32 v41, v0
	v_mov_b32_e32 v42, v0
	v_mov_b32_e32 v43, v0
	v_mov_b32_e32 v44, v0
	v_mov_b32_e32 v45, v0
	v_mov_b32_e32 v46, v0
	v_mov_b32_e32 v47, v0
	v_mov_b32_e32 v48, v0
	v_mov_b32_e32 v49, v0
	v_mov_b32_e32 v50, v0
	v_mov_b32_e32 v51, v0
	v_mov_b32_e32 v52, v0
	v_mov_b32_e32 v53, v0
	v_mov_b32_e32 v54, v0
	v_mov_b32_e32 v55, v0
	v_mov_b32_e32 v56, v0
	v_mov_b32_e32 v57, v0
	v_mov_b32_e32 v58, v0
	v_mov_b32_e32 v59, v0
	v_mov_b32_e32 v60, v0
	v_mov_b32_e32 v61, v0
	v_mov_b32_e32 v62, v0
	v_mov_b32_e32 v63, v0
	v_mov_b32_e32 v64, v0
	v_mov_b32_e32 v65, v0
	v_mov_b32_e32 v66, v0
	v_mov_b32_e32 v67, v0
	v_mov_b32_e32 v68, v0
	v_mov_b32_e32 v69, v0
	v_mov_b32_e32 v70, v0
	v_mov_b32_e32 v71, v0
	v_mov_b32_e32 v72, v0
	v_mov_b32_e32 v73, v0
	v_mov_b32_e32 v74, v0
	v_mov_b32_e32 v75, v0
	v_mov_b32_e32 v76, v0
	v_mov_b32_e32 v77, v0
	v_mov_b32_e32 v78, v0
	v_mov_b32_e32 v79, v0
	v_mov_b32_e32 v80, v0
	v_mov_b32_e32 v81, v0
	v_mov_b32_e32 v82, v0
	v_mov_b32_e32 v83, v0
	v_mov_b32_e32 v84, v0
	v_mov_b32_e32 v85, v0
	v_mov_b32_e32 v86, v0
	v_mov_b32_e32 v87, v0
	v_mov_b32_e32 v88, v0
	v_mov_b32_e32 v89, v0
	v_mov_b32_e32 v90, v0
	v_mov_b32_e32 v91, v0
	v_mov_b32_e32 v92, v0
	v_mov_b32_e32 v93, v0
	v_mov_b32_e32 v94, v0
	v_mov_b32_e32 v95, v0
	v_mov_b32_e32 v96, v0
	v_mov_b32_e32 v97, v0
	v_mov_b32_e32 v98, v0
	v_mov_b32_e32 v99, v0
	v_mov_b32_e32 v100, v0
	v_mov_b32_e32 v101, v0
	v_mov_b32_e32 v102, v0
	v_mov_b32_e32 v103, v0
	v_mov_b32_e32 v104, v0
	v_mov_b32_e32 v105, v0
	v_mov_b32_e32 v106, v0
	v_mov_b32_e32 v107, v0
	v_mov_b32_e32 v108, v0
	v_mov_b32_e32 v109, v0
	v_mov_b32_e32 v110, v0
	v_mov_b32_e32 v111, v0
	v_mov_b32_e32 v112, v0
	v_mov_b32_e32 v113, v0
	v_mov_b32_e32 v114, v0
	v_mov_b32_e32 v115, v0
	v_mov_b32_e32 v116, v0
	v_mov_b32_e32 v117, v0
	v_mov_b32_e32 v118, v0
	v_mov_b32_e32 v119, v0
	v_mov_b32_e32 v120, v0
	v_mov_b32_e32 v121, v0
	v_mov_b32_e32 v122, v0
	v_mov_b32_e32 v123, v0
	v_mov_b32_e32 v124, v0
	v_mov_b32_e32 v125, v0
	v_mov_b32_e32 v126, v0
	v_mov_b32_e32 v127, v0
	.p2align	6

; template <class Epi, class Sched, bool ALIGN_EPI = false, bool SP2 = false>
; __device__ __forceinline__ void gemm_phase(PG8_LAS unsigned char* lds, const Gemm g, const Sched& S, const Epi& E) {
;     ...
;         const bool has_next = S.next(ui + 1, nxt);
;         const char* nA = has_next ? (const char*)g.A + (size_t)nxt.pm * tstep : cA; const char* nB = has_next ? (const char*)g.Bt + (size_t)nxt.pn * tstep : cB;
;         for (int t = 0; t < nt; t += 2) {
;             const bool last = (t == nt - 2);
;             const char* a1 = cA + (size_t)(t + 1) * kstep;
;             const char* a2 = last ? nA : cA + (size_t)(t + 2) * kstep; const char* b2 = last ? nB : cB + (size_t)(t + 2) * kstep;
;             const char* a3 = a2 + kstep; const char* b3 = b2 + kstep;
.LBB0_952:
	s_ashr_i32 s21, s20, 31
	s_lshl_b64 s[22:23], s[20:21], 20
	s_add_u32 s22, s33, s22
	s_addc_u32 s23, s38, s23
	s_and_b64 s[24:25], s[2:3], exec
	s_cselect_b32 s21, s23, s31
	s_cselect_b32 s27, s22, s30
	s_ashr_i32 s19, s18, 31
	s_lshl_b64 s[24:25], s[18:19], 20
	s_add_u32 s24, s39, s24
	s_addc_u32 s25, s40, s25
	s_and_b64 s[36:37], s[2:3], exec
	s_cselect_b32 s19, s25, s35
	s_cselect_b32 s54, s24, s34
	s_add_u32 s30, s30, 0x80080
	s_addc_u32 s31, s31, 0
	s_add_u32 s55, s34, 0x100
	s_addc_u32 s56, s35, 0
	s_mov_b32 s57, -2
	s_waitcnt vmcnt(0)
	.p2align	6

; template <class Epi, class Sched, bool ALIGN_EPI = false, bool SP2 = false>
; __device__ __forceinline__ void gemm_phase(PG8_LAS unsigned char* lds, const Gemm g, const Sched& S, const Epi& E) {
;     ...
;         const bool has_next = S.next(ui + 1, nxt);
;         const char* nA = has_next ? (const char*)g.A + (size_t)nxt.pm * tstep : cA; const char* nB = has_next ? (const char*)g.Bt + (size_t)nxt.pn * tstep : cB;
;         for (int t = 0; t < nt; t += 2) {
;             const bool last = (t == nt - 2);
;             const char* a1 = cA + (size_t)(t + 1) * kstep;
;             const char* a2 = last ? nA : cA + (size_t)(t + 2) * kstep; const char* b2 = last ? nB : cB + (size_t)(t + 2) * kstep;
;             const char* a3 = a2 + kstep; const char* b3 = b2 + kstep;
;     ...
; #pragma unroll
;         for (int a = 0; a < 2; ++a)
; #pragma unroll
;             for (int b = 0; b < 2; ++b)
; #pragma unroll
;                 for (int m = 0; m < 4; ++m)
; #pragma unroll
;                     for (int n = 0; n < 2; ++n) acc[a][b][m][n] = (f32x4){0.f, 0.f, 0.f, 0.f};
.LBB0_1070:
	s_ashr_i32 s21, s20, 31
	s_lshl_b64 s[22:23], s[20:21], 20
	s_add_u32 s22, s38, s22
	s_addc_u32 s23, s39, s23
	s_and_b64 s[24:25], s[2:3], exec
	s_cselect_b32 s21, s23, s31
	s_cselect_b32 s29, s22, s30
	s_ashr_i32 s19, s18, 31
	s_lshl_b64 s[24:25], s[18:19], 20
	s_add_u32 s24, s40, s24
	s_addc_u32 s25, s41, s25
	s_and_b64 s[36:37], s[2:3], exec
	s_cselect_b32 s19, s25, s35
	s_cselect_b32 s55, s24, s34
	s_add_u32 s30, s30, 0x80080
	s_addc_u32 s31, s31, 0
	s_add_u32 s56, s34, 0x100
	v_mov_b32_e32 v0, 0
	s_addc_u32 s57, s35, 0
	s_mov_b32 s58, -2
	v_mov_b32_e32 v1, v0
	v_mov_b32_e32 v2, v0
	v_mov_b32_e32 v3, v0
	v_mov_b32_e32 v4, v0
	v_mov_b32_e32 v5, v0
	v_mov_b32_e32 v6, v0
	v_mov_b32_e32 v7, v0
	v_mov_b32_e32 v8, v0
	v_mov_b32_e32 v9, v0
	v_mov_b32_e32 v10, v0
	v_mov_b32_e32 v11, v0
	v_mov_b32_e32 v12, v0
	v_mov_b32_e32 v13, v0
	v_mov_b32_e32 v14, v0
	v_mov_b32_e32 v15, v0
	v_mov_b32_e32 v16, v0
	v_mov_b32_e32 v17, v0
	v_mov_b32_e32 v18, v0
	v_mov_b32_e32 v19, v0
	v_mov_b32_e32 v20, v0
	v_mov_b32_e32 v21, v0
	v_mov_b32_e32 v22, v0
	v_mov_b32_e32 v23, v0
	v_mov_b32_e32 v24, v0
	v_mov_b32_e32 v25, v0
	v_mov_b32_e32 v26, v0
	v_mov_b32_e32 v27, v0
	v_mov_b32_e32 v28, v0
	v_mov_b32_e32 v29, v0
	v_mov_b32_e32 v30, v0
	v_mov_b32_e32 v31, v0
	v_mov_b32_e32 v32, v0
	v_mov_b32_e32 v33, v0
	v_mov_b32_e32 v34, v0
	v_mov_b32_e32 v35, v0
	v_mov_b32_e32 v36, v0
	v_mov_b32_e32 v37, v0
	v_mov_b32_e32 v38, v0
	v_mov_b32_e32 v39, v0
	v_mov_b32_e32 v40, v0
	v_mov_b32_e32 v41, v0
	v_mov_b32_e32 v42, v0
	v_mov_b32_e32 v43, v0
	v_mov_b32_e32 v44, v0
	v_mov_b32_e32 v45, v0
	v_mov_b32_e32 v46, v0
	v_mov_b32_e32 v47, v0
	v_mov_b32_e32 v48, v0
	v_mov_b32_e32 v49, v0
	v_mov_b32_e32 v50, v0
	v_mov_b32_e32 v51, v0
	v_mov_b32_e32 v52, v0
	v_mov_b32_e32 v53, v0
	v_mov_b32_e32 v54, v0
	v_mov_b32_e32 v55, v0
	v_mov_b32_e32 v56, v0
	v_mov_b32_e32 v57, v0
	v_mov_b32_e32 v58, v0
	v_mov_b32_e32 v59, v0
	v_mov_b32_e32 v60, v0
	v_mov_b32_e32 v61, v0
	v_mov_b32_e32 v62, v0
	v_mov_b32_e32 v63, v0
	v_mov_b32_e32 v64, v0
	v_mov_b32_e32 v65, v0
	v_mov_b32_e32 v66, v0
	v_mov_b32_e32 v67, v0
	v_mov_b32_e32 v68, v0
	v_mov_b32_e32 v69, v0
	v_mov_b32_e32 v70, v0
	v_mov_b32_e32 v71, v0
	v_mov_b32_e32 v72, v0
	v_mov_b32_e32 v73, v0
	v_mov_b32_e32 v74, v0
	v_mov_b32_e32 v75, v0
	v_mov_b32_e32 v76, v0
	v_mov_b32_e32 v77, v0
	v_mov_b32_e32 v78, v0
	v_mov_b32_e32 v79, v0
	v_mov_b32_e32 v80, v0
	v_mov_b32_e32 v81, v0
	v_mov_b32_e32 v82, v0
	v_mov_b32_e32 v83, v0
	v_mov_b32_e32 v84, v0
	v_mov_b32_e32 v85, v0
	v_mov_b32_e32 v86, v0
	v_mov_b32_e32 v87, v0
	v_mov_b32_e32 v88, v0
	v_mov_b32_e32 v89, v0
	v_mov_b32_e32 v90, v0
	v_mov_b32_e32 v91, v0
	v_mov_b32_e32 v92, v0
	v_mov_b32_e32 v93, v0
	v_mov_b32_e32 v94, v0
	v_mov_b32_e32 v95, v0
	v_mov_b32_e32 v96, v0
	v_mov_b32_e32 v97, v0
	v_mov_b32_e32 v98, v0
	v_mov_b32_e32 v99, v0
	v_mov_b32_e32 v100, v0
	v_mov_b32_e32 v101, v0
	v_mov_b32_e32 v102, v0
	v_mov_b32_e32 v103, v0
	v_mov_b32_e32 v104, v0
	v_mov_b32_e32 v105, v0
	v_mov_b32_e32 v106, v0
	v_mov_b32_e32 v107, v0
	v_mov_b32_e32 v108, v0
	v_mov_b32_e32 v109, v0
	v_mov_b32_e32 v110, v0
	v_mov_b32_e32 v111, v0
	v_mov_b32_e32 v112, v0
	v_mov_b32_e32 v113, v0
	v_mov_b32_e32 v114, v0
	v_mov_b32_e32 v115, v0
	v_mov_b32_e32 v116, v0
	v_mov_b32_e32 v117, v0
	v_mov_b32_e32 v118, v0
	v_mov_b32_e32 v119, v0
	v_mov_b32_e32 v120, v0
	v_mov_b32_e32 v121, v0
	v_mov_b32_e32 v122, v0
	v_mov_b32_e32 v123, v0
	v_mov_b32_e32 v124, v0
	v_mov_b32_e32 v125, v0
	v_mov_b32_e32 v126, v0
	v_mov_b32_e32 v127, v0
	.p2align	6

; template <class Epi, class Sched, bool ALIGN_EPI = false, bool SP2 = false>
; __device__ __forceinline__ void gemm_phase(PG8_LAS unsigned char* lds, const Gemm g, const Sched& S, const Epi& E) {
;     ...
;         const bool has_next = S.next(ui + 1, nxt);
;         const char* nA = has_next ? (const char*)g.A + (size_t)nxt.pm * tstep : cA; const char* nB = has_next ? (const char*)g.Bt + (size_t)nxt.pn * tstep : cB;
;         for (int t = 0; t < nt; t += 2) {
;             const bool last = (t == nt - 2);
;             const char* a1 = cA + (size_t)(t + 1) * kstep;
;             const char* a2 = last ? nA : cA + (size_t)(t + 2) * kstep; const char* b2 = last ? nB : cB + (size_t)(t + 2) * kstep;
;             const char* a3 = a2 + kstep; const char* b3 = b2 + kstep;
.LBB0_1342:
	s_ashr_i32 s21, s20, 31
	s_lshl_b64 s[22:23], s[20:21], 21
	s_add_u32 s22, s50, s22
	s_addc_u32 s23, s51, s23
	s_and_b64 s[24:25], s[2:3], exec
	s_cselect_b32 s21, s23, s31
	s_cselect_b32 s27, s22, s30
	s_ashr_i32 s19, s18, 31
	s_lshl_b64 s[24:25], s[18:19], 21
	s_add_u32 s24, s52, s24
	s_addc_u32 s25, s53, s25
	s_and_b64 s[36:37], s[2:3], exec
	s_cselect_b32 s19, s25, s35
	s_cselect_b32 s49, s24, s34
	s_add_u32 s30, s30, 0x100080
	s_addc_u32 s31, s31, 0
	s_add_u32 s54, s34, 0x100
	s_addc_u32 s55, s35, 0
	s_mov_b32 s56, -2
	s_waitcnt vmcnt(0)
	.p2align	6
